# adds XOR swizzle of the attention K image in LDS (removes 8-way bank conflicts of the tile store)
# speedup vs baseline: 1.0217x; 1.0077x over previous
; DI int opaque_lane() { int l; asm volatile("v_mbcnt_lo_u32_b32 %0, -1, 0\n\tv_mbcnt_hi_u32_b32 %0, -1, %0" : "=v"(l)); return l; }
; DI void attn_unit(const bf16_t* Qb, const bf16_t* Kb, const bf16_t* Vt, bf16_t* MIX, int b, int h, int qb, char* lds, int tid_in) {
;     const int lane = opaque_lane(), wave = tid_in >> 6, tid = wave * 64 + lane, r = lane & 31, hh = lane >> 5;
;     const size_t rowbase = (size_t)b * SEQ; const int q0 = qb * 256;
;     bf16x8 qr[6];
;     { const bf16_t* qp = Qb + (rowbase + q0 + 32 * wave + r) * QW + h * 96 + 8 * hh;
; #pragma unroll
;         for (int ds = 0; ds < 6; ++ds) qr[ds] = *(const bf16x8*)(qp + 16 * ds); }
;     f32x16 o0 = {}, o1 = {};
;     float m_run = 0.f, l_run = 0.f;
;     const int NT = 2 * (qb + 1);
;     const bf16_t* Kh = Kb + rowbase * QW + h * 96; const bf16_t* Vh = Vt + (size_t)(b * 8 + h) * 64 * SEQ;
;     float* wsf = (float*)(lds + A_SC) + wave * 32;
;     const int qabs = q0 + 32 * wave + r;
;     u32x4 kreg[3], vreg[2];
;     int kgo[3], klo[3], vgo[2], vlo[2];
; #pragma unroll
;     for (int i = 0; i < 3; ++i) { const int q = tid + 512 * i, kv = q / 12, ck = q % 12; kgo[i] = kv * QW + ck * 8; klo[i] = ck * 2048 + kv * 16; }
; #pragma unroll
;     for (int i = 0; i < 2; ++i) { const int q = tid + 512 * i, d = q >> 4, pc = q & 15; vgo[i] = d * SEQ + pc * 8; vlo[i] = AK_BYTES + d * AV_PITCH + (16 * (pc >> 1) + 4 * (pc & 1)) * 2; }
;     auto gload = [&](int t) {
;         const bf16_t* kt = Kh + (size_t)t * 128 * QW; const bf16_t* vt = Vh + t * 128;
; #pragma unroll
;         for (int i = 0; i < 3; ++i) kreg[i] = *(const u32x4*)(kt + kgo[i]);
; #pragma unroll
;         for (int i = 0; i < 2; ++i) vreg[i] = *(const u32x4*)(vt + vgo[i]);
;     };
;     auto lstore = [&](int buf) {
;         char* bb_ = lds + buf * ABUF;
; #pragma unroll
;         for (int i = 0; i < 3; ++i) *(u32x4*)(bb_ + klo[i]) = kreg[i];
; #pragma unroll
;         for (int i = 0; i < 2; ++i) { u32x2 lo; lo.x = vreg[i].x; lo.y = vreg[i].y; u32x2 hi; hi.x = vreg[i].z; hi.y = vreg[i].w;
;             *(u32x2*)(bb_ + vlo[i]) = lo; *(u32x2*)(bb_ + vlo[i] + 16) = hi; }
;     };
;     gload(0); lstore(0); __syncthreads();
; #pragma unroll
;     for (int ds = 0; ds < 6; ++ds) asm volatile("" : "+v"(qr[ds]));
.LBB0_450:
	s_lshl_b32 s62, s2, 8
	v_mbcnt_lo_u32_b32 v16, -1, 0
	v_mbcnt_hi_u32_b32 v16, -1, v16
	v_lshl_add_u64 v[146:147], v[144:145], 0, s[62:63]
	v_and_b32_e32 v164, 31, v16
	v_or_b32_e32 v0, v146, v164
	v_mov_b64_e32 v[2:3], s[40:41]
	v_mad_u64_u32 v[2:3], s[22:23], v0, s14, v[2:3]
	v_add_u32_e32 v0, v16, v162
	v_mul_hi_i32 v4, v0, s6
	v_lshrrev_b32_e32 v5, 31, v4
	v_ashrrev_i32_e32 v4, 1, v4
	v_add_u32_e32 v17, v4, v5
	v_add_u32_e32 v5, 0x200, v0
	v_mul_hi_i32 v6, v5, s6
	v_lshrrev_b32_e32 v7, 31, v6
	v_ashrrev_i32_e32 v6, 1, v6
	v_add_u32_e32 v19, v6, v7
	v_add_u32_e32 v7, 0x400, v0
	v_mul_hi_i32 v8, v7, s6
	v_lshrrev_b32_e32 v9, 31, v8
	v_ashrrev_i32_e32 v8, 1, v8
	v_mul_lo_u32 v4, v17, 12
	v_add_u32_e32 v21, v8, v9
	v_sub_u32_e32 v18, v0, v4
	v_mul_lo_u32 v4, v17, s18
	v_mul_lo_u32 v6, v19, 12
	v_mul_lo_u32 v8, v21, 12
	v_lshl_add_u32 v4, v18, 3, v4
	v_sub_u32_e32 v20, v5, v6
	v_mul_lo_u32 v6, v19, s18
	v_sub_u32_e32 v22, v7, v8
	v_mul_lo_u32 v7, v21, s18
	v_lshlrev_b32_e32 v23, 3, v16
	v_lshl_add_u32 v6, v20, 3, v6
	v_lshl_add_u32 v8, v22, 3, v7
	v_and_b32_e32 v24, 0x78, v23
	v_ashrrev_i32_e32 v25, 4, v0
	v_ashrrev_i32_e32 v26, 4, v5
	v_ashrrev_i32_e32 v5, 31, v4
	v_lshl_or_b32 v10, v25, 12, v24
	v_lshlrev_b64 v[4:5], 1, v[4:5]
	v_ashrrev_i32_e32 v7, 31, v6
	v_ashrrev_i32_e32 v9, 31, v8
	v_lshl_add_u64 v[12:13], s[44:45], 0, v[4:5]
	v_lshlrev_b64 v[6:7], 1, v[6:7]
	v_lshlrev_b64 v[8:9], 1, v[8:9]
	v_ashrrev_i32_e32 v11, 31, v10
	v_lshl_add_u64 v[14:15], s[44:45], 0, v[6:7]
	global_load_dwordx4 v[98:101], v[12:13], off
	global_load_dwordx4 v[102:105], v[14:15], off
	v_lshl_add_u64 v[12:13], s[44:45], 0, v[8:9]
	v_lshlrev_b64 v[10:11], 1, v[10:11]
	global_load_dwordx4 v[106:109], v[12:13], off
	v_lshl_add_u64 v[12:13], s[42:43], 0, v[10:11]
	global_load_dwordx4 v[110:113], v[12:13], off
	v_lshl_or_b32 v12, v26, 12, v24
	v_ashrrev_i32_e32 v13, 31, v12
	v_lshlrev_b64 v[12:13], 1, v[12:13]
	v_ashrrev_i32_e32 v165, 5, v16
	v_lshl_add_u64 v[14:15], s[42:43], 0, v[12:13]
	global_load_dwordx4 v[114:117], v[14:15], off
	v_lshlrev_b32_e32 v14, 3, v165
	v_mad_i32_i24 v3, v147, s14, v3
	v_ashrrev_i32_e32 v15, 31, v14
	v_lshl_add_u64 v[2:3], v[14:15], 1, v[2:3]
	global_load_dwordx4 v[118:121], v[2:3], off
	global_load_dwordx4 v[122:125], v[2:3], off offset:32
	global_load_dwordx4 v[126:129], v[2:3], off offset:64
	global_load_dwordx4 v[130:133], v[2:3], off offset:96
	global_load_dwordx4 v[134:137], v[2:3], off offset:128
	global_load_dwordx4 v[138:141], v[2:3], off offset:160
	v_lshlrev_b32_e32 v0, 4, v16
	v_and_b32_e32 v0, 0xe0, v0
	v_lshlrev_b32_e32 v2, 4, v17
	v_and_or_b32 v0, v23, 8, v0
	v_lshlrev_b32_e32 v3, 4, v19
	v_lshlrev_b32_e32 v14, 4, v21
	v_lshl_add_u32 v167, v18, 11, v2
	v_mad_u64_u32 v[148:149], s[22:23], v25, s21, v[0:1]
	v_lshl_add_u32 v168, v20, 11, v3
	v_lshl_add_u32 v169, v22, 11, v14
	v_and_b32_e32 v249, 7, v18
	v_lshlrev_b32_e32 v249, 4, v249
	v_xor_b32_e32 v167, v167, v249
	v_and_b32_e32 v249, 7, v20
	v_lshlrev_b32_e32 v249, 4, v249
	v_xor_b32_e32 v168, v168, v249
	v_and_b32_e32 v249, 7, v22
	v_lshlrev_b32_e32 v249, 4, v249
	v_xor_b32_e32 v169, v169, v249
	v_add_u32_e32 v2, 0, v167
	v_mad_u64_u32 v[150:151], s[22:23], v26, s21, v[0:1]
	v_add_u32_e32 v3, 0, v168
	v_add_u32_e32 v14, 0, v169
	v_add_u32_e32 v0, 0, v150
	v_add_u32_e32 v0, 0x6000, v0
	v_mov_b32_e32 v15, v1
	v_lshl_add_u64 v[152:153], s[48:49], 0, v[4:5]
	v_lshl_add_u64 v[154:155], s[48:49], 0, v[6:7]
	v_lshl_add_u64 v[156:157], s[48:49], 0, v[8:9]
	v_lshl_add_u64 v[158:159], s[50:51], 0, v[10:11]
	v_lshl_add_u64 v[160:161], s[50:51], 0, v[12:13]
	v_mov_b32_e32 v4, v1
	v_mov_b32_e32 v5, v1
	v_mov_b32_e32 v6, v1
	v_mov_b32_e32 v7, v1
	v_mov_b32_e32 v8, v1
	v_mov_b32_e32 v9, v1
	v_mov_b32_e32 v10, v1
	s_waitcnt vmcnt(10)
	ds_write_b128 v2, v[98:101]
	s_waitcnt vmcnt(9)
	ds_write_b128 v3, v[102:105]
	s_waitcnt vmcnt(8)
	ds_write_b128 v14, v[106:109]
	v_add_u32_e32 v2, 0, v148
	v_add_u32_e32 v2, 0x6000, v2
	v_mov_b32_e32 v14, v1
	s_waitcnt vmcnt(7)
	ds_write2_b64 v2, v[110:111], v[112:113] offset1:2
	v_mov_b32_e32 v2, v1
	v_mov_b32_e32 v3, v1
	v_mov_b32_e32 v11, v1
	v_mov_b32_e32 v12, v1
	v_mov_b32_e32 v13, v1
	s_waitcnt vmcnt(6)
	ds_write2_b64 v0, v[114:115], v[116:117] offset1:2
	v_mov_b32_e32 v0, v1
	v_mov_b64_e32 v[32:33], v[14:15]
	s_lshl_b32 s61, s2, 1
	v_add_u32_e32 v166, s62, v142
	v_cmp_gt_u32_e64 s[38:39], 32, v16
	v_lshlrev_b32_e32 v176, 4, v165
	v_mov_b64_e32 v[30:31], v[12:13]
	v_mov_b64_e32 v[28:29], v[10:11]
	v_mov_b64_e32 v[26:27], v[8:9]
	v_mov_b64_e32 v[24:25], v[6:7]
	v_mov_b64_e32 v[22:23], v[4:5]
	v_mov_b64_e32 v[20:21], v[2:3]
	v_mov_b64_e32 v[18:19], v[0:1]
	v_mov_b64_e32 v[16:17], v[14:15]
	s_mov_b32 s60, 1
	s_add_i32 s61, s61, 2
	v_or_b32_e32 v170, v164, v166
	v_or_b32_e32 v171, 31, v166
	v_lshlrev_b32_e32 v172, 11, v165
	v_lshlrev_b32_e32 v173, 4, v164
	v_lshlrev_b32_e32 v249, 4, v165
	v_xor_b32_e32 v173, v173, v249
	v_lshlrev_b32_e32 v174, 2, v165
	v_lshl_add_u32 v151, v164, 2, v163
	v_mul_u32_u24_e32 v175, 0x110, v164
	v_add_u32_e32 v149, v163, v176
	s_addk_i32 s62, 0x100
	s_mov_b32 s74, 0
	v_mov_b32_e32 v177, 0
	v_mov_b64_e32 v[14:15], v[12:13]
	v_mov_b64_e32 v[12:13], v[10:11]
	v_mov_b64_e32 v[10:11], v[8:9]
	v_mov_b64_e32 v[8:9], v[6:7]
	v_mov_b64_e32 v[6:7], v[4:5]
	v_mov_b64_e32 v[4:5], v[2:3]
	v_mov_b64_e32 v[2:3], v[0:1]
	v_mov_b32_e32 v0, 0
	s_waitcnt lgkmcnt(0)
	s_barrier
	s_waitcnt vmcnt(5)
	s_waitcnt vmcnt(4)
	s_waitcnt vmcnt(3)
	s_waitcnt vmcnt(2)
	s_waitcnt vmcnt(1)
	s_waitcnt vmcnt(0)
	s_branch .LBB0_452

; DI int crow(int r, int h) { return (r & 3) + 8 * (r >> 2) + 4 * h; }
; #define MFMA32(a, b, c) __builtin_amdgcn_mfma_f32_32x32x16_bf16((a), (b), (c), 0, 0, 0)
; DI void attn_unit(const bf16_t* Qb, const bf16_t* Kb, const bf16_t* Vt, bf16_t* MIX, int b, int h, int qb, char* lds, int tid_in) {
;     ...
;     for (int t = 0; t < NT; ++t) {
;         const int buf = t & 1;
;         if (t + 1 < NT) gload(t + 1);
;         const int kv0 = t * 128;
;         if (kv0 <= q0 + 32 * wave + 31) {
;             const char* kb_ = lds + buf * ABUF; const char* vb_ = kb_ + AK_BYTES;
;             f32x16 p[4];
;             f32x16 negm;
; #pragma unroll
;             for (int i = 0; i < 16; ++i) negm[i] = -m_run;
; #pragma unroll
;             for (int kb = 0; kb < 4; ++kb) p[kb] = negm;
;             {
;                 bf16x8 kf[2][4];
; #pragma unroll
;                 for (int kb = 0; kb < 4; ++kb) kf[0][kb] = *(const bf16x8*)(kb_ + hh * 2048 + (32 * kb + r) * 16);
; #pragma unroll
;                 for (int ds = 0; ds < 6; ++ds) {
;                     if (ds + 1 < 6) {
; #pragma unroll
;                         for (int kb = 0; kb < 4; ++kb) kf[(ds + 1) & 1][kb] = *(const bf16x8*)(kb_ + (2 * (ds + 1) + hh) * 2048 + (32 * kb + r) * 16); }
;                     __builtin_amdgcn_sched_barrier(0);
;                     __builtin_amdgcn_s_setprio(1);
; #pragma unroll
;                     for (int kb = 0; kb < 4; ++kb) p[kb] = MFMA32(kf[ds & 1][kb], qr[ds], p[kb]);
;                     __builtin_amdgcn_s_setprio(0);
;                     __builtin_amdgcn_sched_barrier(0);
;                 }
;             }
;             if (kv0 + 127 > q0 + 32 * wave) {
; #pragma unroll
;                 for (int kb = 0; kb < 4; ++kb)
; #pragma unroll
;                     for (int i = 0; i < 16; ++i) { const int kv = kv0 + 32 * kb + crow(i, hh); if (kv > qabs) p[kb][i] = -1e30f; }
;             }
.LBB0_454:
	s_add_i32 s2, s60, -1
	s_and_b32 s78, s2, 1
	v_cmp_le_i32_e32 vcc, s74, v171
	s_and_saveexec_b64 s[54:55], vcc
	s_cbranch_execz .LBB0_468
	s_mul_i32 s2, s78, 0xa400
	s_add_i32 s16, s2, 0
	v_add3_u32 v211, s16, v172, v173
	v_xor_b32_e32 v250, 32, v211
	v_xor_b32_e32 v251, 64, v211
	v_xor_b32_e32 v252, 0x60, v211
	ds_read_b128 v[50:53], v211
	ds_read_b128 v[54:57], v211 offset:512
	ds_read_b128 v[190:193], v211 offset:1024
	ds_read_b128 v[194:197], v211 offset:1536
	ds_read_b128 v[198:201], v250 offset:4096
	ds_read_b128 v[212:215], v250 offset:4608
	ds_read_b128 v[216:219], v250 offset:5120
	ds_read_b128 v[220:223], v250 offset:5632
	v_xor_b32_e32 v34, 0x80000000, v177
	v_mov_b32_e32 v35, v34
	v_mov_b32_e32 v36, v34
	v_mov_b32_e32 v37, v34
	v_mov_b32_e32 v38, v34
	v_mov_b32_e32 v39, v34
	v_mov_b32_e32 v40, v34
	v_mov_b32_e32 v41, v34
	v_mov_b32_e32 v42, v34
	v_mov_b32_e32 v43, v34
	v_mov_b32_e32 v44, v34
	v_mov_b32_e32 v45, v34
	v_mov_b32_e32 v46, v34
	v_mov_b32_e32 v47, v34
	v_mov_b32_e32 v48, v34
	v_mov_b32_e32 v49, v34
	s_setprio 1
	s_waitcnt lgkmcnt(7)
	v_mfma_f32_32x32x16_bf16 v[82:97], v[50:53], v[118:121], v[34:49]
	s_waitcnt lgkmcnt(6)
	v_mfma_f32_32x32x16_bf16 v[66:81], v[54:57], v[118:121], v[34:49]
	s_waitcnt lgkmcnt(5)
	v_mfma_f32_32x32x16_bf16 v[50:65], v[190:193], v[118:121], v[34:49]
	s_waitcnt lgkmcnt(4)
	v_mfma_f32_32x32x16_bf16 v[34:49], v[194:197], v[118:121], v[34:49]
	s_setprio 0
	ds_read_b128 v[190:193], v251 offset:8192
	ds_read_b128 v[194:197], v251 offset:8704
	ds_read_b128 v[224:227], v251 offset:9216
	ds_read_b128 v[228:231], v251 offset:9728
	s_setprio 1
	s_waitcnt lgkmcnt(7)
	v_mfma_f32_32x32x16_bf16 v[82:97], v[198:201], v[122:125], v[82:97]
	s_waitcnt lgkmcnt(6)
	v_mfma_f32_32x32x16_bf16 v[66:81], v[212:215], v[122:125], v[66:81]
	s_waitcnt lgkmcnt(5)
	v_mfma_f32_32x32x16_bf16 v[50:65], v[216:219], v[122:125], v[50:65]
	s_waitcnt lgkmcnt(4)
	v_mfma_f32_32x32x16_bf16 v[34:49], v[220:223], v[122:125], v[34:49]
	s_setprio 0
	ds_read_b128 v[198:201], v252 offset:12288
	ds_read_b128 v[212:215], v252 offset:12800
	ds_read_b128 v[216:219], v252 offset:13312
	ds_read_b128 v[220:223], v252 offset:13824
	s_setprio 1
	s_waitcnt lgkmcnt(7)
	v_mfma_f32_32x32x16_bf16 v[82:97], v[190:193], v[126:129], v[82:97]
	s_waitcnt lgkmcnt(6)
	v_mfma_f32_32x32x16_bf16 v[66:81], v[194:197], v[126:129], v[66:81]
	s_waitcnt lgkmcnt(5)
	v_mfma_f32_32x32x16_bf16 v[50:65], v[224:227], v[126:129], v[50:65]
	s_waitcnt lgkmcnt(4)
	v_mfma_f32_32x32x16_bf16 v[34:49], v[228:231], v[126:129], v[34:49]
	s_setprio 0
	ds_read_b128 v[190:193], v211 offset:16384
	ds_read_b128 v[194:197], v211 offset:16896
	ds_read_b128 v[224:227], v211 offset:17408
	ds_read_b128 v[228:231], v211 offset:17920
	s_setprio 1
	s_waitcnt lgkmcnt(7)
	v_mfma_f32_32x32x16_bf16 v[82:97], v[198:201], v[130:133], v[82:97]
	s_waitcnt lgkmcnt(6)
	v_mfma_f32_32x32x16_bf16 v[66:81], v[212:215], v[130:133], v[66:81]
	s_waitcnt lgkmcnt(5)
	v_mfma_f32_32x32x16_bf16 v[50:65], v[216:219], v[130:133], v[50:65]
	s_waitcnt lgkmcnt(4)
	v_mfma_f32_32x32x16_bf16 v[34:49], v[220:223], v[130:133], v[34:49]
	s_setprio 0
	ds_read_b128 v[198:201], v250 offset:20480
	ds_read_b128 v[212:215], v250 offset:20992
	ds_read_b128 v[216:219], v250 offset:21504
	ds_read_b128 v[220:223], v250 offset:22016
	s_setprio 1
	s_waitcnt lgkmcnt(7)
	v_mfma_f32_32x32x16_bf16 v[82:97], v[190:193], v[134:137], v[82:97]
	s_waitcnt lgkmcnt(6)
	v_mfma_f32_32x32x16_bf16 v[66:81], v[194:197], v[134:137], v[66:81]
	s_waitcnt lgkmcnt(5)
	v_mfma_f32_32x32x16_bf16 v[50:65], v[224:227], v[134:137], v[50:65]
	s_waitcnt lgkmcnt(4)
	v_mfma_f32_32x32x16_bf16 v[34:49], v[228:231], v[134:137], v[34:49]
	s_setprio 0
	s_setprio 1
	s_waitcnt lgkmcnt(3)
	v_mfma_f32_32x32x16_bf16 v[82:97], v[198:201], v[138:141], v[82:97]
	s_waitcnt lgkmcnt(2)
	v_mfma_f32_32x32x16_bf16 v[66:81], v[212:215], v[138:141], v[66:81]
	s_waitcnt lgkmcnt(1)
	v_mfma_f32_32x32x16_bf16 v[50:65], v[216:219], v[138:141], v[50:65]
	s_waitcnt lgkmcnt(0)
	v_mfma_f32_32x32x16_bf16 v[34:49], v[220:223], v[138:141], v[34:49]
	s_setprio 0
	s_add_i32 s2, s74, 0x7f
	v_cmp_gt_i32_e32 vcc, s2, v166
	s_and_saveexec_b64 s[56:57], vcc
	s_cbranch_execz .LBB0_457
	v_add_u32_e32 v190, s74, v174
	v_cmp_lt_i32_e32 vcc, v190, v170
	v_add_u32_e32 v191, 2, v190
	s_nop 0
	v_cndmask_b32_e32 v83, v208, v83, vcc
	v_cmp_le_i32_e32 vcc, v190, v170
	s_nop 1
	v_cndmask_b32_e32 v82, v208, v82, vcc
	v_cmp_le_i32_e32 vcc, v191, v170
	v_add_u32_e32 v191, 3, v190
	s_nop 0
	v_cndmask_b32_e32 v84, v208, v84, vcc
	v_cmp_le_i32_e32 vcc, v191, v170
	v_add_u32_e32 v191, 8, v190
	s_nop 0
	v_cndmask_b32_e32 v85, v208, v85, vcc
	v_cmp_le_i32_e32 vcc, v191, v170
	v_add_u32_e32 v191, 9, v190
	s_nop 0
	v_cndmask_b32_e32 v86, v208, v86, vcc
	v_cmp_le_i32_e32 vcc, v191, v170
	v_add_u32_e32 v191, 10, v190
	s_nop 0
	v_cndmask_b32_e32 v87, v208, v87, vcc
	v_cmp_le_i32_e32 vcc, v191, v170
	v_add_u32_e32 v191, 11, v190
	s_nop 0
	v_cndmask_b32_e32 v88, v208, v88, vcc
	v_cmp_le_i32_e32 vcc, v191, v170
	v_add_u32_e32 v191, 16, v190
	s_nop 0
	v_cndmask_b32_e32 v89, v208, v89, vcc
	v_cmp_le_i32_e32 vcc, v191, v170
	v_add_u32_e32 v191, 17, v190
	s_nop 0
	v_cndmask_b32_e32 v90, v208, v90, vcc
	v_cmp_le_i32_e32 vcc, v191, v170
	v_add_u32_e32 v191, 18, v190
	s_nop 0
	v_cndmask_b32_e32 v91, v208, v91, vcc
	v_cmp_le_i32_e32 vcc, v191, v170
	v_add_u32_e32 v191, 19, v190
	s_nop 0
	v_cndmask_b32_e32 v92, v208, v92, vcc
	v_cmp_le_i32_e32 vcc, v191, v170
	v_add_u32_e32 v191, 24, v190
	s_nop 0
	v_cndmask_b32_e32 v93, v208, v93, vcc
	v_cmp_le_i32_e32 vcc, v191, v170
	v_add_u32_e32 v191, 25, v190
	s_nop 0
	v_cndmask_b32_e32 v94, v208, v94, vcc
; DI int crow(int r, int h) { return (r & 3) + 8 * (r >> 2) + 4 * h; }
; DI void attn_unit(const bf16_t* Qb, const bf16_t* Kb, const bf16_t* Vt, bf16_t* MIX, int b, int h, int qb, char* lds, int tid_in) {
;     ...
;             if (kv0 + 127 > q0 + 32 * wave) {
; #pragma unroll
;                 for (int kb = 0; kb < 4; ++kb)
; #pragma unroll
;                     for (int i = 0; i < 16; ++i) { const int kv = kv0 + 32 * kb + crow(i, hh); if (kv > qabs) p[kb][i] = -1e30f; }
;             }
	v_cmp_le_i32_e32 vcc, v191, v170
	v_add_u32_e32 v191, 26, v190
	s_nop 0
	v_cndmask_b32_e32 v95, v208, v95, vcc
	v_cmp_le_i32_e32 vcc, v191, v170
	v_add_u32_e32 v191, 27, v190
	s_nop 0
	v_cndmask_b32_e32 v96, v208, v96, vcc
	v_cmp_le_i32_e32 vcc, v191, v170
	v_add_u32_e32 v191, 32, v190
	s_nop 0
	v_cndmask_b32_e32 v97, v208, v97, vcc
	v_cmp_lt_i32_e32 vcc, v191, v170
	s_nop 1
	v_cndmask_b32_e32 v67, v208, v67, vcc
	v_cmp_le_i32_e32 vcc, v191, v170
	v_add_u32_e32 v191, 34, v190
	s_nop 0
	v_cndmask_b32_e32 v66, v208, v66, vcc
	v_cmp_le_i32_e32 vcc, v191, v170
	v_add_u32_e32 v191, 35, v190
	s_nop 0
	v_cndmask_b32_e32 v68, v208, v68, vcc
	v_cmp_le_i32_e32 vcc, v191, v170
	v_add_u32_e32 v191, 40, v190
	s_nop 0
	v_cndmask_b32_e32 v69, v208, v69, vcc
	v_cmp_le_i32_e32 vcc, v191, v170
	v_add_u32_e32 v191, 41, v190
	s_nop 0
	v_cndmask_b32_e32 v70, v208, v70, vcc
	v_cmp_le_i32_e32 vcc, v191, v170
	v_add_u32_e32 v191, 42, v190
	s_nop 0
	v_cndmask_b32_e32 v71, v208, v71, vcc
	v_cmp_le_i32_e32 vcc, v191, v170
	v_add_u32_e32 v191, 43, v190
	s_nop 0
	v_cndmask_b32_e32 v72, v208, v72, vcc
	v_cmp_le_i32_e32 vcc, v191, v170
	v_add_u32_e32 v191, 48, v190
	s_nop 0
	v_cndmask_b32_e32 v73, v208, v73, vcc
	v_cmp_le_i32_e32 vcc, v191, v170
	v_add_u32_e32 v191, 49, v190
	s_nop 0
	v_cndmask_b32_e32 v74, v208, v74, vcc
	v_cmp_le_i32_e32 vcc, v191, v170
	v_add_u32_e32 v191, 50, v190
	s_nop 0
	v_cndmask_b32_e32 v75, v208, v75, vcc
	v_cmp_le_i32_e32 vcc, v191, v170
	v_add_u32_e32 v191, 51, v190
	s_nop 0
	v_cndmask_b32_e32 v76, v208, v76, vcc
	v_cmp_le_i32_e32 vcc, v191, v170
	v_add_u32_e32 v191, 56, v190
	s_nop 0
	v_cndmask_b32_e32 v77, v208, v77, vcc
	v_cmp_le_i32_e32 vcc, v191, v170
	v_add_u32_e32 v191, 57, v190
	s_nop 0
	v_cndmask_b32_e32 v78, v208, v78, vcc
	v_cmp_le_i32_e32 vcc, v191, v170
	v_add_u32_e32 v191, 58, v190
	s_nop 0
	v_cndmask_b32_e32 v79, v208, v79, vcc
	v_cmp_le_i32_e32 vcc, v191, v170
	v_add_u32_e32 v191, 59, v190
	s_nop 0
	v_cndmask_b32_e32 v80, v208, v80, vcc
	v_cmp_le_i32_e32 vcc, v191, v170
	v_add_u32_e32 v191, 64, v190
	s_nop 0
	v_cndmask_b32_e32 v81, v208, v81, vcc
	v_cmp_lt_i32_e32 vcc, v191, v170
	s_nop 1
	v_cndmask_b32_e32 v51, v208, v51, vcc
	v_cmp_le_i32_e32 vcc, v191, v170
	v_add_u32_e32 v191, 0x42, v190
	s_nop 0
	v_cndmask_b32_e32 v50, v208, v50, vcc
	v_cmp_le_i32_e32 vcc, v191, v170
	v_add_u32_e32 v191, 0x43, v190
	s_nop 0
	v_cndmask_b32_e32 v52, v208, v52, vcc
	v_cmp_le_i32_e32 vcc, v191, v170
	v_add_u32_e32 v191, 0x48, v190
	s_nop 0
	v_cndmask_b32_e32 v53, v208, v53, vcc
	v_cmp_le_i32_e32 vcc, v191, v170
	v_add_u32_e32 v191, 0x49, v190
	s_nop 0
	v_cndmask_b32_e32 v54, v208, v54, vcc
	v_cmp_le_i32_e32 vcc, v191, v170
	v_add_u32_e32 v191, 0x4a, v190
	s_nop 0
	v_cndmask_b32_e32 v55, v208, v55, vcc
	v_cmp_le_i32_e32 vcc, v191, v170
	v_add_u32_e32 v191, 0x4b, v190
	s_nop 0
	v_cndmask_b32_e32 v56, v208, v56, vcc
	v_cmp_le_i32_e32 vcc, v191, v170
	v_add_u32_e32 v191, 0x50, v190
	s_nop 0
	v_cndmask_b32_e32 v57, v208, v57, vcc
	v_cmp_le_i32_e32 vcc, v191, v170
	v_add_u32_e32 v191, 0x51, v190
	s_nop 0
	v_cndmask_b32_e32 v58, v208, v58, vcc
	v_cmp_le_i32_e32 vcc, v191, v170
	v_add_u32_e32 v191, 0x52, v190
	s_nop 0
	v_cndmask_b32_e32 v59, v208, v59, vcc
	v_cmp_le_i32_e32 vcc, v191, v170
	v_add_u32_e32 v191, 0x53, v190
	s_nop 0
	v_cndmask_b32_e32 v60, v208, v60, vcc
	v_cmp_le_i32_e32 vcc, v191, v170
	v_add_u32_e32 v191, 0x58, v190
	s_nop 0
	v_cndmask_b32_e32 v61, v208, v61, vcc
	v_cmp_le_i32_e32 vcc, v191, v170
	v_add_u32_e32 v191, 0x59, v190
	s_nop 0
	v_cndmask_b32_e32 v62, v208, v62, vcc
	v_cmp_le_i32_e32 vcc, v191, v170
	v_add_u32_e32 v191, 0x5a, v190
	s_nop 0
	v_cndmask_b32_e32 v63, v208, v63, vcc
	v_cmp_le_i32_e32 vcc, v191, v170
	v_add_u32_e32 v191, 0x5b, v190
	s_nop 0
	v_cndmask_b32_e32 v64, v208, v64, vcc
	v_cmp_le_i32_e32 vcc, v191, v170
	v_add_u32_e32 v191, 0x60, v190
	s_nop 0
	v_cndmask_b32_e32 v65, v208, v65, vcc
	v_cmp_lt_i32_e32 vcc, v191, v170
	s_nop 1
	v_cndmask_b32_e32 v35, v208, v35, vcc
	v_cmp_le_i32_e32 vcc, v191, v170
	v_add_u32_e32 v191, 0x62, v190
	s_nop 0
	v_cndmask_b32_e32 v34, v208, v34, vcc
	v_cmp_le_i32_e32 vcc, v191, v170
	v_add_u32_e32 v191, 0x63, v190
	s_nop 0
	v_cndmask_b32_e32 v36, v208, v36, vcc
	v_cmp_le_i32_e32 vcc, v191, v170
	v_add_u32_e32 v191, 0x68, v190
	s_nop 0
	v_cndmask_b32_e32 v37, v208, v37, vcc
	v_cmp_le_i32_e32 vcc, v191, v170
	v_add_u32_e32 v191, 0x69, v190
	s_nop 0
	v_cndmask_b32_e32 v38, v208, v38, vcc
	v_cmp_le_i32_e32 vcc, v191, v170
	v_add_u32_e32 v191, 0x6a, v190
	s_nop 0
	v_cndmask_b32_e32 v39, v208, v39, vcc
	v_cmp_le_i32_e32 vcc, v191, v170
	v_add_u32_e32 v191, 0x6b, v190
	s_nop 0
	v_cndmask_b32_e32 v40, v208, v40, vcc
	v_cmp_le_i32_e32 vcc, v191, v170
	v_add_u32_e32 v191, 0x70, v190
	s_nop 0
	v_cndmask_b32_e32 v41, v208, v41, vcc
	v_cmp_le_i32_e32 vcc, v191, v170
	v_add_u32_e32 v191, 0x71, v190
	s_nop 0
	v_cndmask_b32_e32 v42, v208, v42, vcc
	v_cmp_le_i32_e32 vcc, v191, v170
	v_add_u32_e32 v191, 0x72, v190
	s_nop 0
	v_cndmask_b32_e32 v43, v208, v43, vcc
	v_cmp_le_i32_e32 vcc, v191, v170
	v_add_u32_e32 v191, 0x73, v190
	s_nop 0
	v_cndmask_b32_e32 v44, v208, v44, vcc
	v_cmp_le_i32_e32 vcc, v191, v170
	v_add_u32_e32 v191, 0x78, v190
	s_nop 0
	v_cndmask_b32_e32 v45, v208, v45, vcc
	v_cmp_le_i32_e32 vcc, v191, v170
	v_add_u32_e32 v191, 0x79, v190
	s_nop 0
	v_cndmask_b32_e32 v46, v208, v46, vcc
	v_cmp_le_i32_e32 vcc, v191, v170
	v_add_u32_e32 v191, 0x7a, v190
	v_add_u32_e32 v190, 0x7b, v190
	v_cndmask_b32_e32 v47, v208, v47, vcc
	v_cmp_le_i32_e32 vcc, v191, v170
	s_nop 1
	v_cndmask_b32_e32 v48, v208, v48, vcc
	v_cmp_le_i32_e32 vcc, v190, v170
	s_nop 1
	v_cndmask_b32_e32 v49, v208, v49, vcc
